# GEMM1 dilated-key epilogue rewritten by hand: SGPR bases + per-lane 32-bit offsets + immediates for the P0, fragment-copy and f32 stores (about 480 instructions per wave instead of 2200), rotary table
# baseline (speedup 1.0000x reference)
.LBB0_315:
	s_andn2_b64 vcc, exec, s[4:5]
	s_cbranch_vccnz .LBB0_485
	s_cmp_lg_u32 s59, 0
	s_cbranch_scc1 .Lepi5_plain
	s_lshl_b32 s39, s90, 8
	s_add_i32 s39, s39, s57
	v_mul_u32_u24_e32 v168, 0x5800, v184
	v_lshl_add_u32 v168, v185, 4, v168
	v_lshlrev_b32_e32 v169, 4, v184
	v_lshl_add_u32 v169, v185, 9, v169
	v_and_b32_e32 v170, 3, v184
	v_lshlrev_b32_e32 v170, 19, v170
	v_lshrrev_b32_e32 v171, 2, v184
	v_lshl_add_u32 v170, v171, 4, v170
	v_lshl_add_u32 v170, v185, 9, v170
	v_lshlrev_b32_e32 v171, 17, v184
	v_lshl_add_u32 v171, v185, 9, v171
	v_add_u32_e32 v172, 0x200000, v169
	v_add_u32_e32 v173, 0x200000, v170
	v_add_u32_e32 v174, 0x200000, v171
	v_lshlrev_b32_e32 v175, 12, v184
	v_lshl_add_u32 v175, v185, 4, v175
	s_mul_i32 s20, s39, 0x5800
	s_lshl_b32 s34, s82, 9
	s_add_u32 s20, s20, s34
	s_lshl_b32 s34, s59, 1
	s_add_u32 s20, s20, s34
	s_add_u32 s4, s0, s20
	s_addc_u32 s5, s1, 0
	s_sub_i32 s34, s82, 28
	s_lshl_b32 s34, s34, 22
	s_lshl_b32 s35, s59, 6
	s_add_u32 s34, s34, s35
	s_lshl_b32 s35, s39, 8
	s_add_u32 s35, s35, s34
	s_add_u32 s6, s88, s35
	s_addc_u32 s7, s89, 0
	s_lshr_b32 s35, s39, 7
	s_lshl_b32 s35, s35, 13
	s_and_b32 s36, s39, 64
	s_lshl_b32 s36, s36, 2
	s_add_u32 s35, s35, s36
	s_add_u32 s35, s35, s34
	s_add_u32 s35, s35, 0x1000000
	s_add_u32 s8, s88, s35
	s_addc_u32 s9, s89, 0
	s_lshr_b32 s35, s39, 9
	s_lshl_b32 s35, s35, 13
	s_lshr_b32 s36, s39, 4
	s_and_b32 s36, s36, 31
	s_lshl_b32 s36, s36, 4
	s_add_u32 s35, s35, s36
	s_add_u32 s35, s35, s34
	s_add_u32 s35, s35, 0x2000000
	s_add_u32 s10, s88, s35
	s_addc_u32 s11, s89, 0
	s_mov_b32 s20, 0x2a00000
	s_cmp_eq_u32 s90, 32
	s_cselect_b32 s20, 0x5500000, s20
	s_lshl_b32 s35, s39, 12
	s_add_u32 s20, s20, s35
	s_sub_i32 s34, s82, 28
	s_lshl_b32 s34, s34, 10
	s_add_u32 s20, s20, s34
	s_lshl_b32 s34, s59, 2
	s_add_u32 s20, s20, s34
	v_readlane_b32 s36, v252, 2
	v_readlane_b32 s37, v252, 3
	s_cmp_lt_u32 s90, 32
	s_cselect_b32 s78, 1, 0
	s_cmp_ge_u32 s90, 24
	s_cselect_b32 s79, 1, 0
	s_add_u32 s36, s36, s20
	s_addc_u32 s37, s37, 0
	s_lshl_b32 s34, s39, 6
	s_add_u32 s86, s16, s34
	s_addc_u32 s87, s17, 0
	s_add_u32 s84, s18, s34
	s_addc_u32 s85, s19, 0
	v_lshlrev_b32_e32 v176, 6, v184
	v_lshl_add_u32 v176, v185, 4, v176
	v_add_u32_e32 v177, 0x2000, v176
	global_load_dwordx4 v[190:193], v176, s[86:87]
	global_load_dwordx4 v[226:229], v176, s[84:85]
	global_load_dwordx4 v[194:197], v176, s[86:87] offset:1024
	global_load_dwordx4 v[230:233], v176, s[84:85] offset:1024
	global_load_dwordx4 v[198:201], v176, s[86:87] offset:2048
	global_load_dwordx4 v[234:237], v176, s[84:85] offset:2048
	global_load_dwordx4 v[202:205], v176, s[86:87] offset:3072
	global_load_dwordx4 v[238:241], v176, s[84:85] offset:3072
	global_load_dwordx4 v[210:213], v177, s[86:87]
	global_load_dwordx4 v[242:245], v177, s[84:85]
	global_load_dwordx4 v[214:217], v177, s[86:87] offset:1024
	global_load_dwordx4 v[246:249], v177, s[84:85] offset:1024
	global_load_dwordx4 v[218:221], v177, s[86:87] offset:2048
	global_load_dwordx4 v[140:143], v177, s[84:85] offset:2048
	global_load_dwordx4 v[222:225], v177, s[86:87] offset:3072
	global_load_dwordx4 v[144:147], v177, s[84:85] offset:3072
	s_waitcnt vmcnt(0)
	s_nop 1
	v_mul_f32_e32 v156, v125, v226
	v_fma_f32 v132, v124, v190, -v156
	v_mul_f32_e32 v156, v124, v226
	v_fma_f32 v136, v125, v190, v156
	v_mul_f32_e32 v156, v127, v227
	v_fma_f32 v133, v126, v191, -v156
	v_mul_f32_e32 v156, v126, v227
	v_fma_f32 v137, v127, v191, v156
	v_mul_f32_e32 v156, v121, v228
	v_fma_f32 v134, v120, v192, -v156
	v_mul_f32_e32 v156, v120, v228
	v_fma_f32 v138, v121, v192, v156
	v_mul_f32_e32 v156, v123, v229
	v_fma_f32 v135, v122, v193, -v156
	v_mul_f32_e32 v156, v122, v229
	v_fma_f32 v139, v123, v193, v156
	v_cvt_pk_bf16_f32 v128, v132, v136
	v_cvt_pk_bf16_f32 v129, v133, v137
	v_cvt_pk_bf16_f32 v130, v134, v138
	v_cvt_pk_bf16_f32 v131, v135, v139
	global_store_dwordx4 v168, v[128:131], s[4:5]
	s_cmp_eq_u32 s78, 0
	s_cbranch_scc1 .Lepi5r_k0_0
	global_store_dwordx4 v169, v[128:131], s[6:7]
	global_store_dwordx4 v170, v[128:131], s[8:9]
	global_store_dwordx4 v171, v[128:131], s[10:11]
.Lepi5r_k0_0:
	s_cmp_eq_u32 s79, 0
	s_cbranch_scc1 .Lepi5r_o0_0
	global_store_dwordx4 v175, v[132:135], s[36:37]
	global_store_dwordx4 v175, v[136:139], s[36:37] offset:64
.Lepi5r_o0_0:
	s_nop 1
	v_mul_f32_e32 v156, v117, v226
	v_fma_f32 v132, v116, v190, -v156
	v_mul_f32_e32 v156, v116, v226
	v_fma_f32 v136, v117, v190, v156
	v_mul_f32_e32 v156, v119, v227
	v_fma_f32 v133, v118, v191, -v156
	v_mul_f32_e32 v156, v118, v227
	v_fma_f32 v137, v119, v191, v156
	v_mul_f32_e32 v156, v113, v228
	v_fma_f32 v134, v112, v192, -v156
	v_mul_f32_e32 v156, v112, v228
	v_fma_f32 v138, v113, v192, v156
	v_mul_f32_e32 v156, v115, v229
	v_fma_f32 v135, v114, v193, -v156
	v_mul_f32_e32 v156, v114, v229
	v_fma_f32 v139, v115, v193, v156
	v_cvt_pk_bf16_f32 v128, v132, v136
	v_cvt_pk_bf16_f32 v129, v133, v137
	v_cvt_pk_bf16_f32 v130, v134, v138
	v_cvt_pk_bf16_f32 v131, v135, v139
	global_store_dwordx4 v168, v[128:131], s[4:5] offset:256
	s_cmp_eq_u32 s78, 0
	s_cbranch_scc1 .Lepi5r_k0_1
	global_store_dwordx4 v172, v[128:131], s[6:7]
	global_store_dwordx4 v173, v[128:131], s[8:9]
	global_store_dwordx4 v174, v[128:131], s[10:11]
.Lepi5r_k0_1:
	s_cmp_eq_u32 s79, 0
	s_cbranch_scc1 .Lepi5r_o0_1
	global_store_dwordx4 v175, v[132:135], s[36:37] offset:512
	global_store_dwordx4 v175, v[136:139], s[36:37] offset:576
.Lepi5r_o0_1:
	s_add_u32 s4, s4, 0x58000
	s_addc_u32 s5, s5, 0
	s_add_u32 s36, s36, 0x10000
	s_addc_u32 s37, s37, 0
	s_nop 1
	v_mul_f32_e32 v156, v109, v230
	v_fma_f32 v132, v108, v194, -v156
	v_mul_f32_e32 v156, v108, v230
	v_fma_f32 v136, v109, v194, v156
	v_mul_f32_e32 v156, v111, v231
	v_fma_f32 v133, v110, v195, -v156
	v_mul_f32_e32 v156, v110, v231
	v_fma_f32 v137, v111, v195, v156
	v_mul_f32_e32 v156, v105, v232
	v_fma_f32 v134, v104, v196, -v156
	v_mul_f32_e32 v156, v104, v232
	v_fma_f32 v138, v105, v196, v156
	v_mul_f32_e32 v156, v107, v233
	v_fma_f32 v135, v106, v197, -v156
	v_mul_f32_e32 v156, v106, v233
	v_fma_f32 v139, v107, v197, v156
	v_cvt_pk_bf16_f32 v128, v132, v136
	v_cvt_pk_bf16_f32 v129, v133, v137
	v_cvt_pk_bf16_f32 v130, v134, v138
	v_cvt_pk_bf16_f32 v131, v135, v139
	global_store_dwordx4 v168, v[128:131], s[4:5]
	s_cmp_eq_u32 s78, 0
	s_cbranch_scc1 .Lepi5r_k1_0
	global_store_dwordx4 v169, v[128:131], s[6:7] offset:256
	global_store_dwordx4 v170, v[128:131], s[8:9] offset:64
	global_store_dwordx4 v171, v[128:131], s[10:11] offset:16

.Lepi5r_o1_0:
	s_nop 1
	v_mul_f32_e32 v156, v101, v230
	v_fma_f32 v132, v100, v194, -v156
	v_mul_f32_e32 v156, v100, v230
	v_fma_f32 v136, v101, v194, v156
	v_mul_f32_e32 v156, v103, v231
	v_fma_f32 v133, v102, v195, -v156
	v_mul_f32_e32 v156, v102, v231
	v_fma_f32 v137, v103, v195, v156
	v_mul_f32_e32 v156, v97, v232
	v_fma_f32 v134, v96, v196, -v156
	v_mul_f32_e32 v156, v96, v232
	v_fma_f32 v138, v97, v196, v156
	v_mul_f32_e32 v156, v99, v233
	v_fma_f32 v135, v98, v197, -v156
	v_mul_f32_e32 v156, v98, v233
	v_fma_f32 v139, v99, v197, v156
	v_cvt_pk_bf16_f32 v128, v132, v136
	v_cvt_pk_bf16_f32 v129, v133, v137
	v_cvt_pk_bf16_f32 v130, v134, v138
	v_cvt_pk_bf16_f32 v131, v135, v139
	global_store_dwordx4 v168, v[128:131], s[4:5] offset:256
	s_cmp_eq_u32 s78, 0
	s_cbranch_scc1 .Lepi5r_k1_1
	global_store_dwordx4 v172, v[128:131], s[6:7] offset:256
	global_store_dwordx4 v173, v[128:131], s[8:9] offset:64
	global_store_dwordx4 v174, v[128:131], s[10:11] offset:16

.Lepi5r_o1_1:
	s_add_u32 s4, s4, 0x58000
	s_addc_u32 s5, s5, 0
	s_add_u32 s36, s36, 0x10000
	s_addc_u32 s37, s37, 0
	s_add_u32 s6, s6, 0x2000
	s_addc_u32 s7, s7, 0
	s_nop 1
	v_mul_f32_e32 v156, v93, v234
	v_fma_f32 v132, v92, v198, -v156
	v_mul_f32_e32 v156, v92, v234
	v_fma_f32 v136, v93, v198, v156
	v_mul_f32_e32 v156, v95, v235
	v_fma_f32 v133, v94, v199, -v156
	v_mul_f32_e32 v156, v94, v235
	v_fma_f32 v137, v95, v199, v156
	v_mul_f32_e32 v156, v89, v236
	v_fma_f32 v134, v88, v200, -v156
	v_mul_f32_e32 v156, v88, v236
	v_fma_f32 v138, v89, v200, v156
	v_mul_f32_e32 v156, v91, v237
	v_fma_f32 v135, v90, v201, -v156
	v_mul_f32_e32 v156, v90, v237
	v_fma_f32 v139, v91, v201, v156
	v_cvt_pk_bf16_f32 v128, v132, v136
	v_cvt_pk_bf16_f32 v129, v133, v137
	v_cvt_pk_bf16_f32 v130, v134, v138
	v_cvt_pk_bf16_f32 v131, v135, v139
	global_store_dwordx4 v168, v[128:131], s[4:5]
	s_cmp_eq_u32 s78, 0
	s_cbranch_scc1 .Lepi5r_k2_0
	global_store_dwordx4 v169, v[128:131], s[6:7]
	global_store_dwordx4 v170, v[128:131], s[8:9] offset:128
	global_store_dwordx4 v171, v[128:131], s[10:11] offset:32

.Lepi5r_o2_0:
	s_nop 1
	v_mul_f32_e32 v156, v85, v234
	v_fma_f32 v132, v84, v198, -v156
	v_mul_f32_e32 v156, v84, v234
	v_fma_f32 v136, v85, v198, v156
	v_mul_f32_e32 v156, v87, v235
	v_fma_f32 v133, v86, v199, -v156
	v_mul_f32_e32 v156, v86, v235
	v_fma_f32 v137, v87, v199, v156
	v_mul_f32_e32 v156, v81, v236
	v_fma_f32 v134, v80, v200, -v156
	v_mul_f32_e32 v156, v80, v236
	v_fma_f32 v138, v81, v200, v156
	v_mul_f32_e32 v156, v83, v237
	v_fma_f32 v135, v82, v201, -v156
	v_mul_f32_e32 v156, v82, v237
	v_fma_f32 v139, v83, v201, v156
	v_cvt_pk_bf16_f32 v128, v132, v136
	v_cvt_pk_bf16_f32 v129, v133, v137
	v_cvt_pk_bf16_f32 v130, v134, v138
	v_cvt_pk_bf16_f32 v131, v135, v139
	global_store_dwordx4 v168, v[128:131], s[4:5] offset:256
	s_cmp_eq_u32 s78, 0
	s_cbranch_scc1 .Lepi5r_k2_1
	global_store_dwordx4 v172, v[128:131], s[6:7]
	global_store_dwordx4 v173, v[128:131], s[8:9] offset:128
	global_store_dwordx4 v174, v[128:131], s[10:11] offset:32

.Lepi5r_o2_1:
	s_add_u32 s4, s4, 0x58000
	s_addc_u32 s5, s5, 0
	s_add_u32 s36, s36, 0x10000
	s_addc_u32 s37, s37, 0
	s_nop 1
	v_mul_f32_e32 v156, v77, v238
	v_fma_f32 v132, v76, v202, -v156
	v_mul_f32_e32 v156, v76, v238
	v_fma_f32 v136, v77, v202, v156
	v_mul_f32_e32 v156, v79, v239
	v_fma_f32 v133, v78, v203, -v156
	v_mul_f32_e32 v156, v78, v239
	v_fma_f32 v137, v79, v203, v156
	v_mul_f32_e32 v156, v73, v240
	v_fma_f32 v134, v72, v204, -v156
	v_mul_f32_e32 v156, v72, v240
	v_fma_f32 v138, v73, v204, v156
	v_mul_f32_e32 v156, v75, v241
	v_fma_f32 v135, v74, v205, -v156
	v_mul_f32_e32 v156, v74, v241
	v_fma_f32 v139, v75, v205, v156
	v_cvt_pk_bf16_f32 v128, v132, v136
	v_cvt_pk_bf16_f32 v129, v133, v137
	v_cvt_pk_bf16_f32 v130, v134, v138
	v_cvt_pk_bf16_f32 v131, v135, v139
	global_store_dwordx4 v168, v[128:131], s[4:5]
	s_cmp_eq_u32 s78, 0
	s_cbranch_scc1 .Lepi5r_k3_0
	global_store_dwordx4 v169, v[128:131], s[6:7] offset:256
	global_store_dwordx4 v170, v[128:131], s[8:9] offset:192
	global_store_dwordx4 v171, v[128:131], s[10:11] offset:48

.Lepi5r_o3_0:
	s_nop 1
	v_mul_f32_e32 v156, v69, v238
	v_fma_f32 v132, v68, v202, -v156
	v_mul_f32_e32 v156, v68, v238
	v_fma_f32 v136, v69, v202, v156
	v_mul_f32_e32 v156, v71, v239
	v_fma_f32 v133, v70, v203, -v156
	v_mul_f32_e32 v156, v70, v239
	v_fma_f32 v137, v71, v203, v156
	v_mul_f32_e32 v156, v65, v240
	v_fma_f32 v134, v64, v204, -v156
	v_mul_f32_e32 v156, v64, v240
	v_fma_f32 v138, v65, v204, v156
	v_mul_f32_e32 v156, v67, v241
	v_fma_f32 v135, v66, v205, -v156
	v_mul_f32_e32 v156, v66, v241
	v_fma_f32 v139, v67, v205, v156
	v_cvt_pk_bf16_f32 v128, v132, v136
	v_cvt_pk_bf16_f32 v129, v133, v137
	v_cvt_pk_bf16_f32 v130, v134, v138
	v_cvt_pk_bf16_f32 v131, v135, v139
	global_store_dwordx4 v168, v[128:131], s[4:5] offset:256
	s_cmp_eq_u32 s78, 0
	s_cbranch_scc1 .Lepi5r_k3_1
	global_store_dwordx4 v172, v[128:131], s[6:7] offset:256
	global_store_dwordx4 v173, v[128:131], s[8:9] offset:192
	global_store_dwordx4 v174, v[128:131], s[10:11] offset:48

.Lepi5r_o3_1:
	s_add_u32 s4, s4, 0x1b8000
	s_addc_u32 s5, s5, 0
	s_add_u32 s36, s36, 0x50000
	s_addc_u32 s37, s37, 0
	s_add_u32 s6, s6, 0x6000
	s_addc_u32 s7, s7, 0
	s_add_u32 s8, s8, 0x2000
	s_addc_u32 s9, s9, 0
	s_cmp_eq_u32 s90, 32
	s_cselect_b32 s79, 0, s79
	s_nop 1
	v_mul_f32_e32 v156, v61, v242
	v_fma_f32 v132, v60, v210, -v156
	v_mul_f32_e32 v156, v60, v242
	v_fma_f32 v136, v61, v210, v156
	v_mul_f32_e32 v156, v63, v243
	v_fma_f32 v133, v62, v211, -v156
	v_mul_f32_e32 v156, v62, v243
	v_fma_f32 v137, v63, v211, v156
	v_mul_f32_e32 v156, v57, v244
	v_fma_f32 v134, v56, v212, -v156
	v_mul_f32_e32 v156, v56, v244
	v_fma_f32 v138, v57, v212, v156
	v_mul_f32_e32 v156, v59, v245
	v_fma_f32 v135, v58, v213, -v156
	v_mul_f32_e32 v156, v58, v245
	v_fma_f32 v139, v59, v213, v156
	v_cvt_pk_bf16_f32 v128, v132, v136
	v_cvt_pk_bf16_f32 v129, v133, v137
	v_cvt_pk_bf16_f32 v130, v134, v138
	v_cvt_pk_bf16_f32 v131, v135, v139
	global_store_dwordx4 v168, v[128:131], s[4:5]
	s_cmp_eq_u32 s78, 0
	s_cbranch_scc1 .Lepi5r_k4_0
	global_store_dwordx4 v169, v[128:131], s[6:7]
	global_store_dwordx4 v170, v[128:131], s[8:9]
	global_store_dwordx4 v171, v[128:131], s[10:11] offset:128

.Lepi5r_o4_0:
	s_nop 1
	v_mul_f32_e32 v156, v53, v242
	v_fma_f32 v132, v52, v210, -v156
	v_mul_f32_e32 v156, v52, v242
	v_fma_f32 v136, v53, v210, v156
	v_mul_f32_e32 v156, v55, v243
	v_fma_f32 v133, v54, v211, -v156
	v_mul_f32_e32 v156, v54, v243
	v_fma_f32 v137, v55, v211, v156
	v_mul_f32_e32 v156, v49, v244
	v_fma_f32 v134, v48, v212, -v156
	v_mul_f32_e32 v156, v48, v244
	v_fma_f32 v138, v49, v212, v156
	v_mul_f32_e32 v156, v51, v245
	v_fma_f32 v135, v50, v213, -v156
	v_mul_f32_e32 v156, v50, v245
	v_fma_f32 v139, v51, v213, v156
	v_cvt_pk_bf16_f32 v128, v132, v136
	v_cvt_pk_bf16_f32 v129, v133, v137
	v_cvt_pk_bf16_f32 v130, v134, v138
	v_cvt_pk_bf16_f32 v131, v135, v139
	global_store_dwordx4 v168, v[128:131], s[4:5] offset:256
	s_cmp_eq_u32 s78, 0
	s_cbranch_scc1 .Lepi5r_k4_1
	global_store_dwordx4 v172, v[128:131], s[6:7]
	global_store_dwordx4 v173, v[128:131], s[8:9]
	global_store_dwordx4 v174, v[128:131], s[10:11] offset:128

.Lepi5r_o4_1:
	s_add_u32 s4, s4, 0x58000
	s_addc_u32 s5, s5, 0
	s_add_u32 s36, s36, 0x10000
	s_addc_u32 s37, s37, 0
	s_nop 1
	v_mul_f32_e32 v156, v45, v246
	v_fma_f32 v132, v44, v214, -v156
	v_mul_f32_e32 v156, v44, v246
	v_fma_f32 v136, v45, v214, v156
	v_mul_f32_e32 v156, v47, v247
	v_fma_f32 v133, v46, v215, -v156
	v_mul_f32_e32 v156, v46, v247
	v_fma_f32 v137, v47, v215, v156
	v_mul_f32_e32 v156, v41, v248
	v_fma_f32 v134, v40, v216, -v156
	v_mul_f32_e32 v156, v40, v248
	v_fma_f32 v138, v41, v216, v156
	v_mul_f32_e32 v156, v43, v249
	v_fma_f32 v135, v42, v217, -v156
	v_mul_f32_e32 v156, v42, v249
	v_fma_f32 v139, v43, v217, v156
	v_cvt_pk_bf16_f32 v128, v132, v136
	v_cvt_pk_bf16_f32 v129, v133, v137
	v_cvt_pk_bf16_f32 v130, v134, v138
	v_cvt_pk_bf16_f32 v131, v135, v139
	global_store_dwordx4 v168, v[128:131], s[4:5]
	s_cmp_eq_u32 s78, 0
	s_cbranch_scc1 .Lepi5r_k5_0
	global_store_dwordx4 v169, v[128:131], s[6:7] offset:256
	global_store_dwordx4 v170, v[128:131], s[8:9] offset:64
	global_store_dwordx4 v171, v[128:131], s[10:11] offset:144

.Lepi5r_o5_0:
	s_nop 1
	v_mul_f32_e32 v156, v37, v246
	v_fma_f32 v132, v36, v214, -v156
	v_mul_f32_e32 v156, v36, v246
	v_fma_f32 v136, v37, v214, v156
	v_mul_f32_e32 v156, v39, v247
	v_fma_f32 v133, v38, v215, -v156
	v_mul_f32_e32 v156, v38, v247
	v_fma_f32 v137, v39, v215, v156
	v_mul_f32_e32 v156, v33, v248
	v_fma_f32 v134, v32, v216, -v156
	v_mul_f32_e32 v156, v32, v248
	v_fma_f32 v138, v33, v216, v156
	v_mul_f32_e32 v156, v35, v249
	v_fma_f32 v135, v34, v217, -v156
	v_mul_f32_e32 v156, v34, v249
	v_fma_f32 v139, v35, v217, v156
	v_cvt_pk_bf16_f32 v128, v132, v136
	v_cvt_pk_bf16_f32 v129, v133, v137
	v_cvt_pk_bf16_f32 v130, v134, v138
	v_cvt_pk_bf16_f32 v131, v135, v139
	global_store_dwordx4 v168, v[128:131], s[4:5] offset:256
	s_cmp_eq_u32 s78, 0
	s_cbranch_scc1 .Lepi5r_k5_1
	global_store_dwordx4 v172, v[128:131], s[6:7] offset:256
	global_store_dwordx4 v173, v[128:131], s[8:9] offset:64
	global_store_dwordx4 v174, v[128:131], s[10:11] offset:144

.Lepi5r_o5_1:
	s_add_u32 s4, s4, 0x58000
	s_addc_u32 s5, s5, 0
	s_add_u32 s36, s36, 0x10000
	s_addc_u32 s37, s37, 0
	s_add_u32 s6, s6, 0x2000
	s_addc_u32 s7, s7, 0
	s_nop 1
	v_mul_f32_e32 v156, v29, v140
	v_fma_f32 v132, v28, v218, -v156
	v_mul_f32_e32 v156, v28, v140
	v_fma_f32 v136, v29, v218, v156
	v_mul_f32_e32 v156, v31, v141
	v_fma_f32 v133, v30, v219, -v156
	v_mul_f32_e32 v156, v30, v141
	v_fma_f32 v137, v31, v219, v156
	v_mul_f32_e32 v156, v25, v142
	v_fma_f32 v134, v24, v220, -v156
	v_mul_f32_e32 v156, v24, v142
	v_fma_f32 v138, v25, v220, v156
	v_mul_f32_e32 v156, v27, v143
	v_fma_f32 v135, v26, v221, -v156
	v_mul_f32_e32 v156, v26, v143
	v_fma_f32 v139, v27, v221, v156
	v_cvt_pk_bf16_f32 v128, v132, v136
	v_cvt_pk_bf16_f32 v129, v133, v137
	v_cvt_pk_bf16_f32 v130, v134, v138
	v_cvt_pk_bf16_f32 v131, v135, v139
	global_store_dwordx4 v168, v[128:131], s[4:5]
	s_cmp_eq_u32 s78, 0
	s_cbranch_scc1 .Lepi5r_k6_0
	global_store_dwordx4 v169, v[128:131], s[6:7]
	global_store_dwordx4 v170, v[128:131], s[8:9] offset:128
	global_store_dwordx4 v171, v[128:131], s[10:11] offset:160

.Lepi5r_o6_0:
	s_nop 1
	v_mul_f32_e32 v156, v21, v140
	v_fma_f32 v132, v20, v218, -v156
	v_mul_f32_e32 v156, v20, v140
	v_fma_f32 v136, v21, v218, v156
	v_mul_f32_e32 v156, v23, v141
	v_fma_f32 v133, v22, v219, -v156
	v_mul_f32_e32 v156, v22, v141
	v_fma_f32 v137, v23, v219, v156
	v_mul_f32_e32 v156, v17, v142
	v_fma_f32 v134, v16, v220, -v156
	v_mul_f32_e32 v156, v16, v142
	v_fma_f32 v138, v17, v220, v156
	v_mul_f32_e32 v156, v19, v143
	v_fma_f32 v135, v18, v221, -v156
	v_mul_f32_e32 v156, v18, v143
	v_fma_f32 v139, v19, v221, v156
	v_cvt_pk_bf16_f32 v128, v132, v136
	v_cvt_pk_bf16_f32 v129, v133, v137
	v_cvt_pk_bf16_f32 v130, v134, v138
	v_cvt_pk_bf16_f32 v131, v135, v139
	global_store_dwordx4 v168, v[128:131], s[4:5] offset:256
	s_cmp_eq_u32 s78, 0
	s_cbranch_scc1 .Lepi5r_k6_1
	global_store_dwordx4 v172, v[128:131], s[6:7]
	global_store_dwordx4 v173, v[128:131], s[8:9] offset:128
	global_store_dwordx4 v174, v[128:131], s[10:11] offset:160

.Lepi5r_o6_1:
	s_add_u32 s4, s4, 0x58000
	s_addc_u32 s5, s5, 0
	s_add_u32 s36, s36, 0x10000
	s_addc_u32 s37, s37, 0
	s_nop 1
	v_mul_f32_e32 v156, v13, v144
	v_fma_f32 v132, v12, v222, -v156
	v_mul_f32_e32 v156, v12, v144
	v_fma_f32 v136, v13, v222, v156
	v_mul_f32_e32 v156, v15, v145
	v_fma_f32 v133, v14, v223, -v156
	v_mul_f32_e32 v156, v14, v145
	v_fma_f32 v137, v15, v223, v156
	v_mul_f32_e32 v156, v9, v146
	v_fma_f32 v134, v8, v224, -v156
	v_mul_f32_e32 v156, v8, v146
	v_fma_f32 v138, v9, v224, v156
	v_mul_f32_e32 v156, v11, v147
	v_fma_f32 v135, v10, v225, -v156
	v_mul_f32_e32 v156, v10, v147
	v_fma_f32 v139, v11, v225, v156
	v_cvt_pk_bf16_f32 v128, v132, v136
	v_cvt_pk_bf16_f32 v129, v133, v137
	v_cvt_pk_bf16_f32 v130, v134, v138
	v_cvt_pk_bf16_f32 v131, v135, v139
	global_store_dwordx4 v168, v[128:131], s[4:5]
	s_cmp_eq_u32 s78, 0
	s_cbranch_scc1 .Lepi5r_k7_0
	global_store_dwordx4 v169, v[128:131], s[6:7] offset:256
	global_store_dwordx4 v170, v[128:131], s[8:9] offset:192
	global_store_dwordx4 v171, v[128:131], s[10:11] offset:176

.Lepi5r_o7_0:
	s_nop 1
	v_mul_f32_e32 v156, v5, v144
	v_fma_f32 v132, v4, v222, -v156
	v_mul_f32_e32 v156, v4, v144
	v_fma_f32 v136, v5, v222, v156
	v_mul_f32_e32 v156, v7, v145
	v_fma_f32 v133, v6, v223, -v156
	v_mul_f32_e32 v156, v6, v145
	v_fma_f32 v137, v7, v223, v156
	v_mul_f32_e32 v156, v1, v146
	v_fma_f32 v134, v0, v224, -v156
	v_mul_f32_e32 v156, v0, v146
	v_fma_f32 v138, v1, v224, v156
	v_mul_f32_e32 v156, v3, v147
	v_fma_f32 v135, v2, v225, -v156
	v_mul_f32_e32 v156, v2, v147
	v_fma_f32 v139, v3, v225, v156
	v_cvt_pk_bf16_f32 v128, v132, v136
	v_cvt_pk_bf16_f32 v129, v133, v137
	v_cvt_pk_bf16_f32 v130, v134, v138
	v_cvt_pk_bf16_f32 v131, v135, v139
	global_store_dwordx4 v168, v[128:131], s[4:5] offset:256
	s_cmp_eq_u32 s78, 0
	s_cbranch_scc1 .Lepi5r_k7_1
	global_store_dwordx4 v172, v[128:131], s[6:7] offset:256
	global_store_dwordx4 v173, v[128:131], s[8:9] offset:192
	global_store_dwordx4 v174, v[128:131], s[10:11] offset:176

.Lepi5_plain:
	s_lshl_b32 s39, s90, 8
	s_add_i32 s39, s39, s57
	v_mul_u32_u24_e32 v168, 0x5800, v184
	v_lshl_add_u32 v168, v185, 4, v168
	v_lshlrev_b32_e32 v169, 4, v184
	v_lshl_add_u32 v169, v185, 9, v169
	v_and_b32_e32 v170, 3, v184
	v_lshlrev_b32_e32 v170, 19, v170
	v_lshrrev_b32_e32 v171, 2, v184
	v_lshl_add_u32 v170, v171, 4, v170
	v_lshl_add_u32 v170, v185, 9, v170
	v_lshlrev_b32_e32 v171, 17, v184
	v_lshl_add_u32 v171, v185, 9, v171
	v_add_u32_e32 v172, 0x200000, v169
	v_add_u32_e32 v173, 0x200000, v170
	v_add_u32_e32 v174, 0x200000, v171
	v_lshlrev_b32_e32 v175, 12, v184
	v_lshl_add_u32 v175, v185, 5, v175
	s_mul_i32 s20, s39, 0x5800
	s_lshl_b32 s34, s82, 9
	s_add_u32 s20, s20, s34
	s_lshl_b32 s34, s59, 1
	s_add_u32 s20, s20, s34
	s_add_u32 s4, s0, s20
	s_addc_u32 s5, s1, 0
	s_sub_i32 s34, s82, 28
	s_lshl_b32 s34, s34, 22
	s_lshl_b32 s35, s59, 6
	s_add_u32 s34, s34, s35
	s_lshl_b32 s35, s39, 8
	s_add_u32 s35, s35, s34
	s_add_u32 s6, s88, s35
	s_addc_u32 s7, s89, 0
	s_lshr_b32 s35, s39, 7
	s_lshl_b32 s35, s35, 13
	s_and_b32 s36, s39, 64
	s_lshl_b32 s36, s36, 2
	s_add_u32 s35, s35, s36
	s_add_u32 s35, s35, s34
	s_add_u32 s35, s35, 0x1000000
	s_add_u32 s8, s88, s35
	s_addc_u32 s9, s89, 0
	s_lshr_b32 s35, s39, 9
	s_lshl_b32 s35, s35, 13
	s_lshr_b32 s36, s39, 4
	s_and_b32 s36, s36, 31
	s_lshl_b32 s36, s36, 4
	s_add_u32 s35, s35, s36
	s_add_u32 s35, s35, s34
	s_add_u32 s35, s35, 0x2000000
	s_add_u32 s10, s88, s35
	s_addc_u32 s11, s89, 0
	s_mov_b32 s20, 0x2a00000
	s_cmp_eq_u32 s90, 32
	s_cselect_b32 s20, 0x5500000, s20
	s_lshl_b32 s35, s39, 12
	s_add_u32 s20, s20, s35
	s_sub_i32 s34, s82, 28
	s_lshl_b32 s34, s34, 10
	s_add_u32 s20, s20, s34
	s_lshl_b32 s34, s59, 2
	s_add_u32 s20, s20, s34
	v_readlane_b32 s36, v252, 2
	v_readlane_b32 s37, v252, 3
	s_cmp_lt_u32 s90, 32
	s_cselect_b32 s78, 1, 0
	s_cmp_ge_u32 s90, 24
	s_cselect_b32 s79, 1, 0
	s_add_u32 s36, s36, s20
	s_addc_u32 s37, s37, 0
	s_nop 1
	v_cvt_pk_bf16_f32 v128, v124, v125
	v_cvt_pk_bf16_f32 v129, v126, v127
	v_cvt_pk_bf16_f32 v130, v120, v121
	v_cvt_pk_bf16_f32 v131, v122, v123
	global_store_dwordx4 v168, v[128:131], s[4:5]
	s_cmp_eq_u32 s78, 0
	s_cbranch_scc1 .Lepi5p_k0_0
	global_store_dwordx4 v169, v[128:131], s[6:7]
	global_store_dwordx4 v170, v[128:131], s[8:9]
	global_store_dwordx4 v171, v[128:131], s[10:11]
.Lepi5p_k0_0:
	s_cmp_eq_u32 s79, 0
	s_cbranch_scc1 .Lepi5p_o0_0
	global_store_dwordx4 v175, v[124:127], s[36:37]
	global_store_dwordx4 v175, v[120:123], s[36:37] offset:16
.Lepi5p_o0_0:
	s_nop 1
	v_cvt_pk_bf16_f32 v128, v116, v117
	v_cvt_pk_bf16_f32 v129, v118, v119
	v_cvt_pk_bf16_f32 v130, v112, v113
	v_cvt_pk_bf16_f32 v131, v114, v115
	global_store_dwordx4 v168, v[128:131], s[4:5] offset:256
	s_cmp_eq_u32 s78, 0
	s_cbranch_scc1 .Lepi5p_k0_1
	global_store_dwordx4 v172, v[128:131], s[6:7]
	global_store_dwordx4 v173, v[128:131], s[8:9]
	global_store_dwordx4 v174, v[128:131], s[10:11]
.Lepi5p_k0_1:
	s_cmp_eq_u32 s79, 0
	s_cbranch_scc1 .Lepi5p_o0_1
	global_store_dwordx4 v175, v[116:119], s[36:37] offset:512
	global_store_dwordx4 v175, v[112:115], s[36:37] offset:528
.Lepi5p_o0_1:
	s_add_u32 s4, s4, 0x58000
	s_addc_u32 s5, s5, 0
	s_add_u32 s36, s36, 0x10000
	s_addc_u32 s37, s37, 0
	s_nop 1
	v_cvt_pk_bf16_f32 v128, v108, v109
	v_cvt_pk_bf16_f32 v129, v110, v111
	v_cvt_pk_bf16_f32 v130, v104, v105
	v_cvt_pk_bf16_f32 v131, v106, v107
	global_store_dwordx4 v168, v[128:131], s[4:5]
	s_cmp_eq_u32 s78, 0
	s_cbranch_scc1 .Lepi5p_k1_0
	global_store_dwordx4 v169, v[128:131], s[6:7] offset:256
	global_store_dwordx4 v170, v[128:131], s[8:9] offset:64
	global_store_dwordx4 v171, v[128:131], s[10:11] offset:16
.Lepi5p_k1_0:
	s_cmp_eq_u32 s79, 0
	s_cbranch_scc1 .Lepi5p_o1_0
	global_store_dwordx4 v175, v[108:111], s[36:37]
	global_store_dwordx4 v175, v[104:107], s[36:37] offset:16
.Lepi5p_o1_0:
	s_nop 1
	v_cvt_pk_bf16_f32 v128, v100, v101
	v_cvt_pk_bf16_f32 v129, v102, v103
	v_cvt_pk_bf16_f32 v130, v96, v97
	v_cvt_pk_bf16_f32 v131, v98, v99
	global_store_dwordx4 v168, v[128:131], s[4:5] offset:256
	s_cmp_eq_u32 s78, 0
	s_cbranch_scc1 .Lepi5p_k1_1
	global_store_dwordx4 v172, v[128:131], s[6:7] offset:256
	global_store_dwordx4 v173, v[128:131], s[8:9] offset:64
	global_store_dwordx4 v174, v[128:131], s[10:11] offset:16
.Lepi5p_k1_1:
	s_cmp_eq_u32 s79, 0
	s_cbranch_scc1 .Lepi5p_o1_1
	global_store_dwordx4 v175, v[100:103], s[36:37] offset:512
	global_store_dwordx4 v175, v[96:99], s[36:37] offset:528
.Lepi5p_o1_1:
	s_add_u32 s4, s4, 0x58000
	s_addc_u32 s5, s5, 0
	s_add_u32 s36, s36, 0x10000
	s_addc_u32 s37, s37, 0
	s_add_u32 s6, s6, 0x2000
	s_addc_u32 s7, s7, 0
	s_nop 1
	v_cvt_pk_bf16_f32 v128, v92, v93
	v_cvt_pk_bf16_f32 v129, v94, v95
	v_cvt_pk_bf16_f32 v130, v88, v89
	v_cvt_pk_bf16_f32 v131, v90, v91
	global_store_dwordx4 v168, v[128:131], s[4:5]
	s_cmp_eq_u32 s78, 0
	s_cbranch_scc1 .Lepi5p_k2_0
	global_store_dwordx4 v169, v[128:131], s[6:7]
	global_store_dwordx4 v170, v[128:131], s[8:9] offset:128
	global_store_dwordx4 v171, v[128:131], s[10:11] offset:32
.Lepi5p_k2_0:
	s_cmp_eq_u32 s79, 0
	s_cbranch_scc1 .Lepi5p_o2_0
	global_store_dwordx4 v175, v[92:95], s[36:37]
	global_store_dwordx4 v175, v[88:91], s[36:37] offset:16
.Lepi5p_o2_0:
	s_nop 1
	v_cvt_pk_bf16_f32 v128, v84, v85
	v_cvt_pk_bf16_f32 v129, v86, v87
	v_cvt_pk_bf16_f32 v130, v80, v81
	v_cvt_pk_bf16_f32 v131, v82, v83
	global_store_dwordx4 v168, v[128:131], s[4:5] offset:256
	s_cmp_eq_u32 s78, 0
	s_cbranch_scc1 .Lepi5p_k2_1
	global_store_dwordx4 v172, v[128:131], s[6:7]
	global_store_dwordx4 v173, v[128:131], s[8:9] offset:128
	global_store_dwordx4 v174, v[128:131], s[10:11] offset:32
.Lepi5p_k2_1:
	s_cmp_eq_u32 s79, 0
	s_cbranch_scc1 .Lepi5p_o2_1
	global_store_dwordx4 v175, v[84:87], s[36:37] offset:512
	global_store_dwordx4 v175, v[80:83], s[36:37] offset:528
.Lepi5p_o2_1:
	s_add_u32 s4, s4, 0x58000
	s_addc_u32 s5, s5, 0
	s_add_u32 s36, s36, 0x10000
	s_addc_u32 s37, s37, 0
	s_nop 1
	v_cvt_pk_bf16_f32 v128, v76, v77
	v_cvt_pk_bf16_f32 v129, v78, v79
	v_cvt_pk_bf16_f32 v130, v72, v73
	v_cvt_pk_bf16_f32 v131, v74, v75
	global_store_dwordx4 v168, v[128:131], s[4:5]
	s_cmp_eq_u32 s78, 0
	s_cbranch_scc1 .Lepi5p_k3_0
	global_store_dwordx4 v169, v[128:131], s[6:7] offset:256
	global_store_dwordx4 v170, v[128:131], s[8:9] offset:192
	global_store_dwordx4 v171, v[128:131], s[10:11] offset:48
.Lepi5p_k3_0:
	s_cmp_eq_u32 s79, 0
	s_cbranch_scc1 .Lepi5p_o3_0
	global_store_dwordx4 v175, v[76:79], s[36:37]
	global_store_dwordx4 v175, v[72:75], s[36:37] offset:16
.Lepi5p_o3_0:
	s_nop 1
	v_cvt_pk_bf16_f32 v128, v68, v69
	v_cvt_pk_bf16_f32 v129, v70, v71
	v_cvt_pk_bf16_f32 v130, v64, v65
	v_cvt_pk_bf16_f32 v131, v66, v67
	global_store_dwordx4 v168, v[128:131], s[4:5] offset:256
	s_cmp_eq_u32 s78, 0
	s_cbranch_scc1 .Lepi5p_k3_1
	global_store_dwordx4 v172, v[128:131], s[6:7] offset:256
	global_store_dwordx4 v173, v[128:131], s[8:9] offset:192
	global_store_dwordx4 v174, v[128:131], s[10:11] offset:48
.Lepi5p_k3_1:
	s_cmp_eq_u32 s79, 0
	s_cbranch_scc1 .Lepi5p_o3_1
	global_store_dwordx4 v175, v[68:71], s[36:37] offset:512
	global_store_dwordx4 v175, v[64:67], s[36:37] offset:528
.Lepi5p_o3_1:
	s_add_u32 s4, s4, 0x1b8000
	s_addc_u32 s5, s5, 0
	s_add_u32 s36, s36, 0x50000
	s_addc_u32 s37, s37, 0
	s_add_u32 s6, s6, 0x6000
	s_addc_u32 s7, s7, 0
	s_add_u32 s8, s8, 0x2000
	s_addc_u32 s9, s9, 0
	s_cmp_eq_u32 s90, 32
	s_cselect_b32 s79, 0, s79
	s_nop 1
	v_cvt_pk_bf16_f32 v128, v60, v61
	v_cvt_pk_bf16_f32 v129, v62, v63
	v_cvt_pk_bf16_f32 v130, v56, v57
	v_cvt_pk_bf16_f32 v131, v58, v59
	global_store_dwordx4 v168, v[128:131], s[4:5]
	s_cmp_eq_u32 s78, 0
	s_cbranch_scc1 .Lepi5p_k4_0
	global_store_dwordx4 v169, v[128:131], s[6:7]
	global_store_dwordx4 v170, v[128:131], s[8:9]
	global_store_dwordx4 v171, v[128:131], s[10:11] offset:128
.Lepi5p_k4_0:
	s_cmp_eq_u32 s79, 0
	s_cbranch_scc1 .Lepi5p_o4_0
	global_store_dwordx4 v175, v[60:63], s[36:37]
	global_store_dwordx4 v175, v[56:59], s[36:37] offset:16
.Lepi5p_o4_0:
	s_nop 1
	v_cvt_pk_bf16_f32 v128, v52, v53
	v_cvt_pk_bf16_f32 v129, v54, v55
	v_cvt_pk_bf16_f32 v130, v48, v49
	v_cvt_pk_bf16_f32 v131, v50, v51
	global_store_dwordx4 v168, v[128:131], s[4:5] offset:256
	s_cmp_eq_u32 s78, 0
	s_cbranch_scc1 .Lepi5p_k4_1
	global_store_dwordx4 v172, v[128:131], s[6:7]
	global_store_dwordx4 v173, v[128:131], s[8:9]
	global_store_dwordx4 v174, v[128:131], s[10:11] offset:128
.Lepi5p_k4_1:
	s_cmp_eq_u32 s79, 0
	s_cbranch_scc1 .Lepi5p_o4_1
	global_store_dwordx4 v175, v[52:55], s[36:37] offset:512
	global_store_dwordx4 v175, v[48:51], s[36:37] offset:528
.Lepi5p_o4_1:
	s_add_u32 s4, s4, 0x58000
	s_addc_u32 s5, s5, 0
	s_add_u32 s36, s36, 0x10000
	s_addc_u32 s37, s37, 0
	s_nop 1
	v_cvt_pk_bf16_f32 v128, v44, v45
	v_cvt_pk_bf16_f32 v129, v46, v47
	v_cvt_pk_bf16_f32 v130, v40, v41
	v_cvt_pk_bf16_f32 v131, v42, v43
	global_store_dwordx4 v168, v[128:131], s[4:5]
	s_cmp_eq_u32 s78, 0
	s_cbranch_scc1 .Lepi5p_k5_0
	global_store_dwordx4 v169, v[128:131], s[6:7] offset:256
	global_store_dwordx4 v170, v[128:131], s[8:9] offset:64
	global_store_dwordx4 v171, v[128:131], s[10:11] offset:144
.Lepi5p_k5_0:
	s_cmp_eq_u32 s79, 0
	s_cbranch_scc1 .Lepi5p_o5_0
	global_store_dwordx4 v175, v[44:47], s[36:37]
	global_store_dwordx4 v175, v[40:43], s[36:37] offset:16
.Lepi5p_o5_0:
	s_nop 1
	v_cvt_pk_bf16_f32 v128, v36, v37
	v_cvt_pk_bf16_f32 v129, v38, v39
	v_cvt_pk_bf16_f32 v130, v32, v33
	v_cvt_pk_bf16_f32 v131, v34, v35
	global_store_dwordx4 v168, v[128:131], s[4:5] offset:256
	s_cmp_eq_u32 s78, 0
	s_cbranch_scc1 .Lepi5p_k5_1
	global_store_dwordx4 v172, v[128:131], s[6:7] offset:256
	global_store_dwordx4 v173, v[128:131], s[8:9] offset:64
	global_store_dwordx4 v174, v[128:131], s[10:11] offset:144
.Lepi5p_k5_1:
	s_cmp_eq_u32 s79, 0
	s_cbranch_scc1 .Lepi5p_o5_1
	global_store_dwordx4 v175, v[36:39], s[36:37] offset:512
	global_store_dwordx4 v175, v[32:35], s[36:37] offset:528
.Lepi5p_o5_1:
	s_add_u32 s4, s4, 0x58000
	s_addc_u32 s5, s5, 0
	s_add_u32 s36, s36, 0x10000
	s_addc_u32 s37, s37, 0
	s_add_u32 s6, s6, 0x2000
	s_addc_u32 s7, s7, 0
	s_nop 1
	v_cvt_pk_bf16_f32 v128, v28, v29
	v_cvt_pk_bf16_f32 v129, v30, v31
	v_cvt_pk_bf16_f32 v130, v24, v25
	v_cvt_pk_bf16_f32 v131, v26, v27
	global_store_dwordx4 v168, v[128:131], s[4:5]
	s_cmp_eq_u32 s78, 0
	s_cbranch_scc1 .Lepi5p_k6_0
	global_store_dwordx4 v169, v[128:131], s[6:7]
	global_store_dwordx4 v170, v[128:131], s[8:9] offset:128
	global_store_dwordx4 v171, v[128:131], s[10:11] offset:160
.Lepi5p_k6_0:
	s_cmp_eq_u32 s79, 0
	s_cbranch_scc1 .Lepi5p_o6_0
	global_store_dwordx4 v175, v[28:31], s[36:37]
	global_store_dwordx4 v175, v[24:27], s[36:37] offset:16
.Lepi5p_o6_0:
	s_nop 1
	v_cvt_pk_bf16_f32 v128, v20, v21
	v_cvt_pk_bf16_f32 v129, v22, v23
	v_cvt_pk_bf16_f32 v130, v16, v17
	v_cvt_pk_bf16_f32 v131, v18, v19
	global_store_dwordx4 v168, v[128:131], s[4:5] offset:256
	s_cmp_eq_u32 s78, 0
	s_cbranch_scc1 .Lepi5p_k6_1
	global_store_dwordx4 v172, v[128:131], s[6:7]
	global_store_dwordx4 v173, v[128:131], s[8:9] offset:128
	global_store_dwordx4 v174, v[128:131], s[10:11] offset:160
.Lepi5p_k6_1:
	s_cmp_eq_u32 s79, 0
	s_cbranch_scc1 .Lepi5p_o6_1
	global_store_dwordx4 v175, v[20:23], s[36:37] offset:512
	global_store_dwordx4 v175, v[16:19], s[36:37] offset:528
.Lepi5p_o6_1:
	s_add_u32 s4, s4, 0x58000
	s_addc_u32 s5, s5, 0
	s_add_u32 s36, s36, 0x10000
	s_addc_u32 s37, s37, 0
	s_nop 1
	v_cvt_pk_bf16_f32 v128, v12, v13
	v_cvt_pk_bf16_f32 v129, v14, v15
	v_cvt_pk_bf16_f32 v130, v8, v9
	v_cvt_pk_bf16_f32 v131, v10, v11
	global_store_dwordx4 v168, v[128:131], s[4:5]
	s_cmp_eq_u32 s78, 0
	s_cbranch_scc1 .Lepi5p_k7_0
	global_store_dwordx4 v169, v[128:131], s[6:7] offset:256
	global_store_dwordx4 v170, v[128:131], s[8:9] offset:192
	global_store_dwordx4 v171, v[128:131], s[10:11] offset:176
.Lepi5p_k7_0:
	s_cmp_eq_u32 s79, 0
	s_cbranch_scc1 .Lepi5p_o7_0
	global_store_dwordx4 v175, v[12:15], s[36:37]
	global_store_dwordx4 v175, v[8:11], s[36:37] offset:16
.Lepi5p_o7_0:
	s_nop 1
	v_cvt_pk_bf16_f32 v128, v4, v5
	v_cvt_pk_bf16_f32 v129, v6, v7
	v_cvt_pk_bf16_f32 v130, v0, v1
	v_cvt_pk_bf16_f32 v131, v2, v3
	global_store_dwordx4 v168, v[128:131], s[4:5] offset:256
	s_cmp_eq_u32 s78, 0
	s_cbranch_scc1 .Lepi5p_k7_1
	global_store_dwordx4 v172, v[128:131], s[6:7] offset:256
	global_store_dwordx4 v173, v[128:131], s[8:9] offset:192
	global_store_dwordx4 v174, v[128:131], s[10:11] offset:176
.Lepi5p_k7_1:
	s_cmp_eq_u32 s79, 0
	s_cbranch_scc1 .Lepi5p_o7_1
	global_store_dwordx4 v175, v[4:7], s[36:37] offset:512
	global_store_dwordx4 v175, v[0:3], s[36:37] offset:528
.Lepi5p_o7_1:
.Lepi5_done:
.LBB0_485:
	s_mov_b64 s[4:5], 0
